# static priority raise (s_setprio 1) for waves 4..7 during the S5 scan items (pass 1 and pass 2): the two waves of a SIMD no longer stall in step
# speedup vs baseline: 1.0000x; 1.0000x over previous
.LBB0_193:
	s_or_b64 exec, exec, s[14:15]
	s_setprio 0
	s_add_i32 s8, s8, s60
	s_cmpk_gt_i32 s8, 0xff
	s_cbranch_scc1 .LBB0_225
.LBB0_194:
	s_ashr_i32 s9, s8, 3
	s_and_b32 s4, s8, 7
	s_waitcnt vmcnt(0) lgkmcnt(0)
	s_barrier
	v_readlane_b32 s98, v240, 55
	s_nop 0
	s_bitcmp1_b32 s98, 8
	s_cbranch_scc0 .Lp2_noprio
	s_setprio 1
.Lp2_noprio:
	s_and_saveexec_b64 s[14:15], s[12:13]
	s_movk_i32 s5, 0x110
	s_movk_i32 s33, 0xdff
	s_cbranch_execz .LBB0_197
	s_lshl_b32 s38, s4, 8
	s_mov_b32 s39, 0
	s_lshl_b32 s3, s9, 8
	v_lshl_add_u64 v[0:1], v[172:173], 0, s[38:39]
	v_ashrrev_i32_e32 v3, 4, v210
	v_add_u32_e32 v4, s3, v3
	v_ashrrev_i32_e32 v5, 31, v4
	v_lshlrev_b64 v[4:5], 11, v[4:5]
	v_lshl_add_u64 v[4:5], v[0:1], 0, v[4:5]
	s_mov_b64 s[34:35], 0x10000
	v_mad_u64_u32 v[8:9], vcc, v3, s5, v[174:175]
	global_load_dwordx4 v[100:103], v[4:5], off
	v_lshl_add_u64 v[4:5], v[4:5], 0, s[34:35]
	global_load_dwordx4 v[104:107], v[4:5], off
	v_lshl_add_u64 v[4:5], v[4:5], 0, s[34:35]
	global_load_dwordx4 v[108:111], v[4:5], off
	v_lshl_add_u64 v[4:5], v[4:5], 0, s[34:35]
	global_load_dwordx4 v[112:115], v[4:5], off
	v_lshl_add_u64 v[4:5], v[4:5], 0, s[34:35]
	global_load_dwordx4 v[116:119], v[4:5], off
	v_lshl_add_u64 v[4:5], v[4:5], 0, s[34:35]
	global_load_dwordx4 v[120:123], v[4:5], off
	v_lshl_add_u64 v[4:5], v[4:5], 0, s[34:35]
	global_load_dwordx4 v[124:127], v[4:5], off
	v_lshl_add_u64 v[4:5], v[4:5], 0, s[34:35]
	global_load_dwordx4 v[128:131], v[4:5], off
	s_waitcnt vmcnt(7)
	ds_write_b128 v8, v[100:103]
	s_waitcnt vmcnt(6)
	ds_write_b128 v8, v[104:107] offset:8704
	s_waitcnt vmcnt(5)
	ds_write_b128 v8, v[108:111] offset:17408
	s_waitcnt vmcnt(4)
	ds_write_b128 v8, v[112:115] offset:26112
	s_waitcnt vmcnt(3)
	ds_write_b128 v8, v[116:119] offset:34816
	s_waitcnt vmcnt(2)
	ds_write_b128 v8, v[120:123] offset:43520
	s_waitcnt vmcnt(1)
	ds_write_b128 v8, v[124:127] offset:52224
	s_waitcnt vmcnt(0)
	ds_write_b128 v8, v[128:131] offset:60928

.LBB0_255:
	s_ashr_i32 s14, s13, 3
	s_and_b32 s15, s13, 7
	s_waitcnt vmcnt(0) lgkmcnt(0)
	s_barrier
	v_readlane_b32 s98, v240, 55
	s_nop 0
	s_bitcmp1_b32 s98, 8
	s_cbranch_scc0 .Lp1_noprio
	s_setprio 1
.Lp1_noprio:
	s_and_saveexec_b64 s[8:9], s[4:5]
	s_movk_i32 s19, 0x110
	s_movk_i32 s33, 0xdff
	s_cbranch_execz .LBB0_258
	s_lshl_b32 s34, s15, 8
	s_mov_b32 s35, 0
	s_lshl_b32 s18, s14, 8
	v_lshl_add_u64 v[0:1], v[116:117], 0, s[34:35]
	v_ashrrev_i32_e32 v3, 4, v210
	v_add_u32_e32 v4, s18, v3
	v_ashrrev_i32_e32 v5, 31, v4
	v_lshlrev_b64 v[4:5], 11, v[4:5]
	v_lshl_add_u64 v[4:5], v[0:1], 0, v[4:5]
	s_mov_b64 s[10:11], 0x10000
	v_mad_u64_u32 v[8:9], vcc, v3, s19, v[118:119]
	global_load_dwordx4 v[80:83], v[4:5], off
	v_lshl_add_u64 v[4:5], v[4:5], 0, s[10:11]
	global_load_dwordx4 v[84:87], v[4:5], off
	v_lshl_add_u64 v[4:5], v[4:5], 0, s[10:11]
	global_load_dwordx4 v[88:91], v[4:5], off
	v_lshl_add_u64 v[4:5], v[4:5], 0, s[10:11]
	global_load_dwordx4 v[92:95], v[4:5], off
	v_lshl_add_u64 v[4:5], v[4:5], 0, s[10:11]
	global_load_dwordx4 v[96:99], v[4:5], off
	v_lshl_add_u64 v[4:5], v[4:5], 0, s[10:11]
	global_load_dwordx4 v[100:103], v[4:5], off
	v_lshl_add_u64 v[4:5], v[4:5], 0, s[10:11]
	global_load_dwordx4 v[104:107], v[4:5], off
	v_lshl_add_u64 v[4:5], v[4:5], 0, s[10:11]
	global_load_dwordx4 v[108:111], v[4:5], off
	s_waitcnt vmcnt(7)
	ds_write_b128 v8, v[80:83]
	s_waitcnt vmcnt(6)
	ds_write_b128 v8, v[84:87] offset:8704
	s_waitcnt vmcnt(5)
	ds_write_b128 v8, v[88:91] offset:17408
	s_waitcnt vmcnt(4)
	ds_write_b128 v8, v[92:95] offset:26112
	s_waitcnt vmcnt(3)
	ds_write_b128 v8, v[96:99] offset:34816
	s_waitcnt vmcnt(2)
	ds_write_b128 v8, v[100:103] offset:43520
	s_waitcnt vmcnt(1)
	ds_write_b128 v8, v[104:107] offset:52224
	s_waitcnt vmcnt(0)
	ds_write_b128 v8, v[108:111] offset:60928

.LBB0_261:
	s_setprio 0
	s_mov_b32 s80, s38
	s_mov_b64 s[84:85], s[46:47]
	s_waitcnt vmcnt(0) lgkmcnt(0)
	s_barrier
